# barrier-5 wait moved to the second merge-phase epilogue (P4 outputs are first needed by the fourth unit)
# speedup vs baseline: 1.0015x; 1.0015x over previous
; template <int PH> DI bool get_unit(const Params& p, int i, Unit& u, int mode) {
;     ...
;         if (mode == 0) {
;             const int gi = i / 6, s = i - gi * 6, L = gi * G + c;
;             if (L >= 256) return false;
;             static_order(L, 64, 4, 256, pm, pn);
;             br = s >> 1; isup = s & 1; u.aux = 0;
; __global__ void __launch_bounds__(512, 2) fwd_megakernel(Params p) {
;     ...
;     gemm_phase<5>(p, lds, 0);
.Lsb_arr_done:
	s_or_b64 exec, exec, s[4:5]
	s_mov_b32 s100, 2
	v_mov_b32_e32 v10, v203
	s_waitcnt lgkmcnt(0)
	s_barrier
	s_load_dwordx2 s[8:9], s[0:1], 0xc8
	s_cmpk_lt_i32 s2, 0x100
	s_cselect_b64 s[12:13], -1, 0
	s_cmpk_gt_i32 s2, 0xff
	v_readfirstlane_b32 s11, v10
	s_cbranch_scc1 .LBB0_1200
	s_ashr_i32 s4, s2, 31
	s_lshr_b32 s4, s4, 29
	s_add_i32 s6, s2, s4
	s_and_b32 s4, s6, -8
	s_sub_i32 s7, s2, s4
	s_cmp_gt_i32 s7, -1
	s_cbranch_scc0 .LBB0_1201
	s_lshl_b32 s10, s7, 5
	s_cbranch_execz .LBB0_1202
	s_branch .LBB0_1203

; #define G_BAR __builtin_amdgcn_s_barrier()
; DI unsigned xb_ld(unsigned* p)              { return __hip_atomic_load(p, __ATOMIC_RELAXED, __HIP_MEMORY_SCOPE_AGENT); }
; #define XB_SPIN(cond, bar) do { unsigned _sp = 0; while (cond) { __builtin_amdgcn_s_sleep(1); \
;     if ((++_sp & 255u) == 0u) { if (xb_ld(&(bar)[XB_TMO])) break; if (_sp > XB_SPIN_CAP) { atomicAdd(&(bar)[XB_TMO], 1u); break; } } } } while (0)
; template <int PH>
; DI void gemm_phase(const Params& p, LAS unsigned char* lds, int mode) {
;     ...
;         if (GEMM_ALIGN) { if (wr == 0) G_BAR; }
;         epilogue<PH>(p, acc, cur, wr, wc, fr, fq);
; DI void xcd_barrier(const XcdBarrier& b) {
;     ...
;         } else {
;             XB_SPIN(xb_ld(&bar[XB_XGEN(b.x)]) == gen, bar);
.LBB0_1230:
	s_cmp_eq_u32 s100, 0
	s_cbranch_scc1 .Lsb_done
	s_sub_i32 s100, s100, 1
	s_cmp_eq_u32 s100, 0
	s_cbranch_scc0 .Lsb_done
	s_mov_b32 s100, 0
	v_cmp_eq_u32_e32 vcc, 0, v203
	s_and_saveexec_b64 s[40:41], vcc
	s_cbranch_execz .Lsb_join
	s_lshl_b32 s76, s33, 8
	s_add_u32 s76, s46, s76
	s_addc_u32 s77, s47, 0
	s_mov_b32 s42, 0
	s_cmp_eq_u32 s101, 2
	s_cbranch_scc1 .Lsb_lead_go
	s_cmp_eq_u32 s101, 1
	s_cbranch_scc1 .Lsb_lead_wait
	v_mov_b32_e32 v160, 0x3100
